# EpiUp rewritten by hand: A tile rows permuted so a lane holds 4 consecutive rows, conv taps from registers (packed FMA), halo by DPP mov + LDS, packed silu gate, dwordx4 ACT stores
# speedup vs baseline: 1.0304x; 1.0304x over previous
.LBB0_670:
	s_or_b64 exec, exec, s[10:11]
	v_readlane_b32 s10, v254, 12
	s_mov_b64 s[14:15], s[84:85]
	s_mov_b64 s[16:17], s[84:85]
	v_mov_b32_e32 v3, v208
	v_readlane_b32 s11, v254, 13
	s_waitcnt lgkmcnt(0)
	s_barrier
	s_and_b64 vcc, exec, s[10:11]
	v_readfirstlane_b32 s7, v3
	s_cbranch_vccz .LBB0_756
	v_lshlrev_b32_e32 v1, 4, v3
	v_add_u32_e32 v0, 0x2000, v1
	v_ashrrev_i32_e32 v4, 31, v0
	v_lshrrev_b32_e32 v4, 22, v4
	v_add_u32_e32 v4, v0, v4
	v_ashrrev_i32_e32 v12, 10, v4
	v_mul_i32_i24_e32 v4, 0x400, v12
	v_sub_u32_e32 v0, v0, v4
	v_lshrrev_b32_e32 v4, 4, v0
	s_ashr_i32 s18, s7, 6
	v_bitop3_b32 v0, v4, v0, 32 bitop3:0x6c
	s_ashr_i32 s6, s7, 8
	s_lshl_b32 s54, s18, 10
	v_ashrrev_i32_e32 v4, 31, v0
	s_add_u32 s19, s8, 0x3e00000
	v_lshrrev_b32_e32 v4, 26, v4
	s_addc_u32 s93, s9, 0
	s_mul_i32 s10, s36, 0xb00000
	v_add_u32_e32 v4, v0, v4
	v_lshlrev_b32_e32 v5, 3, v12
	s_add_u32 s10, s8, s10
	v_ashrrev_i32_e32 v13, 6, v4
	v_and_b32_e32 v5, -16, v5
	s_addc_u32 s11, s9, 0
	v_add_u32_e32 v5, v13, v5
	s_add_u32 s55, s10, 0xe00000
	v_and_b32_e32 v6, 3, v13
	s_mov_b32 s10, 0x1fffe0
	v_lshrrev_b32_e32 v7, 2, v5
	v_lshlrev_b32_e32 v8, 1, v5
	v_and_b32_e32 v4, 0xc0, v4
	v_and_or_b32 v6, v5, s10, v6
	v_and_b32_e32 v7, 4, v7
	v_and_b32_e32 v8, 24, v8
	v_sub_u32_e32 v0, v0, v4
	v_or3_b32 v6, v6, v7, v8
	v_lshlrev_b32_e32 v7, 5, v12
	v_ashrrev_i16_sdwa v0, v210, sext(v0) dst_sel:DWORD dst_unused:UNUSED_PAD src0_sel:DWORD src1_sel:BYTE_0
	v_and_b32_e32 v7, 32, v7
	v_bfe_i32 v14, v0, 0, 16
	v_add_lshl_u32 v4, v7, v14, 1
	v_lshl_add_u32 v0, v6, 11, v4
	v_and_b32_e32 v18, 15, v5
	v_bfe_u32 v19, v5, 4, 2
	v_lshl_or_b32 v18, v18, 2, v19
	v_and_b32_e32 v19, 64, v5
	v_or_b32_e32 v18, v18, v19
	v_lshl_add_u32 v170, v18, 11, v4
	v_bfe_i32 v4, v3, 27, 1
	v_lshrrev_b32_e32 v4, 22, v4
	v_add_u32_e32 v4, v1, v4
	v_and_b32_e32 v4, 0xfffffc00, v4
	v_sub_u32_e32 v1, v1, v4
	v_lshrrev_b32_e32 v4, 4, v1
	v_ashrrev_i32_e32 v5, 31, v3
	v_bitop3_b32 v1, v4, v1, 32 bitop3:0x6c
	v_lshrrev_b32_e32 v5, 26, v5
	v_ashrrev_i32_e32 v4, 31, v1
	v_add_u32_e32 v5, v3, v5
	v_lshrrev_b32_e32 v4, 26, v4
	v_ashrrev_i32_e32 v16, 6, v5
	v_add_u32_e32 v4, v1, v4
	v_lshlrev_b32_e32 v5, 3, v16
	v_ashrrev_i32_e32 v15, 6, v4
	v_and_b32_e32 v5, -16, v5
	v_add_u32_e32 v5, v15, v5
	v_and_b32_e32 v6, 3, v15
	v_lshrrev_b32_e32 v7, 2, v5
	v_lshlrev_b32_e32 v8, 1, v5
	v_and_b32_e32 v4, 0xc0, v4
	v_writelane_b32 v253, s70, 17
	v_and_or_b32 v6, v5, s10, v6
	v_and_b32_e32 v7, 4, v7
	v_and_b32_e32 v8, 24, v8
	v_sub_u32_e32 v1, v1, v4
	v_writelane_b32 v253, s71, 18
	s_addc_u32 s70, s11, 0
	v_or3_b32 v6, v6, v7, v8
	v_lshlrev_b32_e32 v7, 5, v16
	v_ashrrev_i16_sdwa v1, v210, sext(v1) dst_sel:DWORD dst_unused:UNUSED_PAD src0_sel:DWORD src1_sel:BYTE_0
	v_readlane_b32 s10, v254, 37
	v_and_b32_e32 v7, 32, v7
	v_bfe_i32 v17, v1, 0, 16
	v_readlane_b32 s11, v254, 38
	s_add_u32 s12, s55, s10
	v_add_lshl_u32 v1, v7, v17, 1
	s_addc_u32 s13, s70, s11
	s_add_i32 s71, s54, 0
	v_lshl_add_u32 v172, v6, 11, v1
	s_add_i32 m0, s71, 0x10000
	v_and_b32_e32 v18, 15, v5
	v_bfe_u32 v19, v5, 4, 2
	v_lshl_or_b32 v18, v18, 2, v19
	v_and_b32_e32 v19, 64, v5
	v_or_b32_e32 v18, v18, v19
	v_lshl_add_u32 v174, v18, 11, v1
	global_load_lds_dwordx4 v172, s[12:13]
	s_add_i32 m0, s71, 0x12000
	s_add_u32 s10, s12, 0x40000
	global_load_lds_dwordx4 v0, s[12:13]
	s_addc_u32 s11, s13, 0
	s_add_i32 m0, s71, 0x14000
	v_writelane_b32 v253, s19, 11
	global_load_lds_dwordx4 v172, s[10:11]
	s_add_i32 m0, s71, 0x16000
	v_mov_b32_e32 v173, v2
	global_load_lds_dwordx4 v0, s[10:11]
	v_readlane_b32 s10, v254, 35
	v_readlane_b32 s11, v254, 36
	s_add_u32 s10, s19, s10
	s_addc_u32 s11, s93, s11
	s_add_i32 s72, s71, 0x2000
	s_mov_b32 m0, s71
	s_add_u32 s20, s10, 0x40000
	global_load_lds_dwordx4 v174, s[10:11]
	s_mov_b32 m0, s72
	s_addc_u32 s21, s11, 0
	s_add_i32 s73, s71, 0x4000
	global_load_lds_dwordx4 v170, s[10:11]
	s_mov_b32 m0, s73
	s_add_i32 s78, s71, 0x6000
	global_load_lds_dwordx4 v174, s[20:21]
	s_mov_b32 m0, s78
	s_cmp_eq_u32 s6, 1
	global_load_lds_dwordx4 v170, s[20:21]
	s_load_dwordx2 s[14:15], s[14:15], 0x60
	s_nop 0
	s_load_dwordx2 s[16:17], s[16:17], 0x68
	v_mov_b32_e32 v1, v2
	v_mov_b32_e32 v175, v2
	v_mov_b32_e32 v171, v2
	s_cselect_b64 s[20:21], -1, 0
	v_lshl_add_u64 v[8:9], s[12:13], 0, v[172:173]
	v_lshl_add_u64 v[6:7], s[12:13], 0, v[0:1]
	v_lshl_add_u64 v[4:5], s[10:11], 0, v[174:175]
	v_writelane_b32 v253, s20, 13
	s_cmp_lg_u32 s6, 1
	v_lshl_add_u64 v[10:11], s[10:11], 0, v[170:171]
	v_writelane_b32 v253, s21, 14
	s_cbranch_scc1 .LBB0_673
	s_barrier
.LBB0_673:
	s_add_u32 s20, s8, 0xbe00000
	s_addc_u32 s21, s9, 0
	s_mul_i32 s19, s36, 0x10800
	s_waitcnt lgkmcnt(0)
	s_add_u32 s14, s14, s19
	s_addc_u32 s15, s15, 0
	s_mul_i32 s19, s36, 0x5800
	s_add_u32 s16, s16, s19
	s_addc_u32 s17, s17, 0
	s_add_u32 s22, s8, 0x3100000
	s_addc_u32 s23, s9, 0
	v_bfe_u32 v206, v3, 4, 2
	s_add_u32 s24, s8, 0x3700000
	v_and_b32_e32 v157, 15, v3
	v_lshlrev_b32_e32 v18, 4, v206
	v_lshlrev_b32_e32 v19, 2, v3
	s_addc_u32 s25, s9, 0
	s_and_b32 s18, s18, 3
	v_lshl_or_b32 v18, v157, 6, v18
	s_lshl_b32 s8, s6, 13
	v_and_b32_e32 v19, 32, v19
	s_add_i32 m0, s71, 0x18000
	v_lshl_add_u64 v[8:9], v[8:9], 0, s[76:77]
	s_lshl_b32 s79, s6, 6
	v_bitop3_b32 v20, v18, s8, v19 bitop3:0xde
	s_lshl_b32 s84, s18, 5
	s_lshl_b32 s8, s18, 12
	s_waitcnt vmcnt(2)
	s_barrier
	global_load_lds_dwordx4 v[8:9], off
	v_lshl_add_u64 v[6:7], v[6:7], 0, s[76:77]
	s_add_i32 m0, s71, 0x1a000
	s_add_i32 s85, s71, 0x8000
	s_add_i32 s86, s71, 0xa000
	v_bitop3_b32 v207, v18, s8, v19 bitop3:0xde
	global_load_lds_dwordx4 v[6:7], off
	v_lshl_add_u64 v[4:5], v[4:5], 0, s[76:77]
	s_mov_b32 m0, s85
	s_add_u32 s8, s12, 0x40080
	global_load_lds_dwordx4 v[4:5], off
	v_lshl_add_u64 v[4:5], v[10:11], 0, s[76:77]
	s_mov_b32 m0, s86
	s_addc_u32 s9, s13, 0
	global_load_lds_dwordx4 v[4:5], off
	s_add_i32 m0, s71, 0x1c000
	v_lshl_add_u64 v[4:5], s[8:9], 0, v[172:173]
	global_load_lds_dwordx4 v[4:5], off
	v_lshl_add_u64 v[4:5], s[8:9], 0, v[0:1]
	s_add_i32 m0, s71, 0x1e000
	s_movk_i32 s8, 0x1600
	global_load_lds_dwordx4 v[4:5], off
	v_ashrrev_i32_e32 v4, 7, v3
	v_cmp_gt_i32_e32 vcc, 3, v4
	v_mul_lo_u32 v4, v4, s8
	v_ashrrev_i32_e32 v5, 31, v4
	v_lshl_add_u64 v[4:5], v[4:5], 2, s[14:15]
	v_mov_b32_e32 v6, s17
	v_cndmask_b32_e32 v177, v6, v5, vcc
	v_mov_b32_e32 v5, s16
	v_cndmask_b32_e32 v176, v5, v4, vcc
	v_bfe_i32 v4, v3, 6, 1
	v_lshlrev_b32_e32 v3, 1, v3
	s_cmpk_lt_u32 s7, 0x100
	v_and_b32_e32 v3, 0x7e, v3
	s_movk_i32 s8, 0xb00
	s_cselect_b64 s[26:27], -1, 0
	s_cmpk_gt_u32 s7, 0xff
	v_and_or_b32 v219, v4, s8, v3
	s_cselect_b64 s[28:29], -1, 0
	s_and_b32 s7, s7, 0xffffff00
	s_lshl_b32 s8, s18, 6
	s_or_b32 s87, s8, s7
	s_lshl_b32 s7, s6, 11
	s_add_i32 s9, 0, 0x20000
	s_lshl_b32 s8, s18, 9
	s_add_i32 s92, s9, s7
	s_add_i32 s92, s92, s8
	v_lshlrev_b32_e32 v3, 14, v16
	s_cmp_eq_u32 s6, 3
	v_and_b32_e32 v3, 0xffff8000, v3
	s_cselect_b64 s[30:31], -1, 0
	s_add_i32 s6, s6, 2
	v_lshl_add_u32 v3, v15, 11, v3
	v_and_b32_e32 v4, 1, v16
	s_cmp_eq_u32 s6, 0
	v_lshl_or_b32 v3, v4, 6, v3
	s_cselect_b64 s[34:35], -1, 0
	s_cmp_lg_u32 s6, 0
	v_mov_b32_e32 v178, v174
	v_lshlrev_b32_e32 v3, 14, v12
	s_cselect_b64 s[36:37], -1, 0
	s_cmp_eq_u32 s6, 3
	v_and_b32_e32 v3, 0xffff8000, v3
	s_cselect_b64 s[38:39], -1, 0
	s_lshl_b32 s6, s6, 11
	v_lshl_add_u32 v3, v13, 11, v3
	v_and_b32_e32 v4, 1, v12
	s_waitcnt vmcnt(6)
	s_add_i32 s94, s9, s6
	v_lshl_or_b32 v3, v4, 6, v3
	s_add_i32 s6, s92, 0xfffff800
	s_add_i32 s94, s94, s8
	v_mov_b32_e32 v180, v170
	v_mov_b32_e32 v3, v2
	s_mov_b32 s16, 0
	v_writelane_b32 v253, s6, 15
	s_add_i32 s6, s94, 0xfffff800
	v_mov_b32_e32 v179, v2
	v_mov_b32_e32 v181, v2
	v_add_u32_e32 v220, 0, v20
	v_mov_b64_e32 v[182:183], v[2:3]
	v_readlane_b32 s48, v254, 33
	v_readlane_b32 s19, v254, 15
	s_mov_b32 s7, 0
	s_barrier
	v_readlane_b32 s49, v254, 34
	s_branch .LBB0_676

.LBB0_684:
	v_lshlrev_b32_e32 v132, 4, v206
	v_add3_u32 v133, s87, v157, v132
	v_lshlrev_b32_e32 v133, 3, v133
	v_add_u32_e32 v133, 0x22800, v133
	s_lshl_b32 s10, s16, 10
	s_lshl_b32 s11, s79, 2
	s_add_i32 s10, s10, s11
	s_add_i32 s10, s10, 0x23800
	v_lshl_add_u32 v154, v157, 4, s10
	ds_read_b128 v[150:153], v154
	ds_read_b128 v[158:161], v154 offset:512
	s_waitcnt vmcnt(0)
	ds_write_b64 v133, v[182:183]
	v_add_u32_e32 v155, s92, v132
	v_lshlrev_b32_e32 v204, 5, v206
	s_lshl_b32 s11, s84, 2
	s_add_i32 s11, s11, 0x22800
	v_add_u32_e32 v204, s11, v204
	v_add_u32_e32 v205, 0xfffff800, v155
	v_lshlrev_b32_e32 v221, 9, v157
	v_add_u32_e32 v221, v221, v132
	v_lshlrev_b32_e32 v3, 5, v206
	v_cmp_eq_u32_e64 s[56:57], 15, v157
	s_mul_i32 s14, s48, 0x160000
	s_lshl_b32 s15, s19, 9
	s_add_i32 s14, s14, s15
	s_lshr_b32 s15, s84, 6
	s_lshl_b32 s15, s15, 15
	s_add_i32 s14, s14, s15
	s_lshl_b32 s15, s79, 7
	s_add_i32 s14, s14, s15
	s_and_b32 s15, s84, 32
	s_lshl_b32 s15, s15, 1
	s_add_i32 s14, s14, s15
	s_add_u32 s14, s20, s14
	s_addc_u32 s15, s21, 0
	s_add_u32 s50, s14, 0x4000
	s_addc_u32 s51, s15, 0
	s_mul_i32 s41, s48, 0xb000
	s_lshl_b32 s49, s19, 3
	s_add_i32 s41, s41, s49
	s_lshl_b32 s49, s84, 2
	s_add_i32 s41, s41, s49
	s_mov_b32 s10, 0xbfb8aa3b
	s_mov_b32 s11, 0xbfb8aa3b
	s_mov_b32 s12, 1.0
	s_mov_b32 s13, 1.0
	s_waitcnt lgkmcnt(0)
	v_pk_mul_f32 v[120:121], v[120:121], v[152:153] op_sel_hi:[1,0]
	v_pk_mul_f32 v[122:123], v[122:123], v[152:153] op_sel_hi:[1,0]
	v_pk_mul_f32 v[116:117], v[116:117], v[152:153] op_sel:[0,1]
	v_pk_mul_f32 v[118:119], v[118:119], v[152:153] op_sel:[0,1]
	v_pk_mul_f32 v[104:105], v[104:105], v[152:153] op_sel_hi:[1,0]
	v_pk_mul_f32 v[106:107], v[106:107], v[152:153] op_sel_hi:[1,0]
	v_pk_mul_f32 v[100:101], v[100:101], v[152:153] op_sel:[0,1]
	v_pk_mul_f32 v[102:103], v[102:103], v[152:153] op_sel:[0,1]
	v_pk_mul_f32 v[88:89], v[88:89], v[152:153] op_sel_hi:[1,0]
	v_pk_mul_f32 v[90:91], v[90:91], v[152:153] op_sel_hi:[1,0]
	v_pk_mul_f32 v[84:85], v[84:85], v[152:153] op_sel:[0,1]
	v_pk_mul_f32 v[86:87], v[86:87], v[152:153] op_sel:[0,1]
	v_pk_mul_f32 v[72:73], v[72:73], v[152:153] op_sel_hi:[1,0]
	v_pk_mul_f32 v[74:75], v[74:75], v[152:153] op_sel_hi:[1,0]
	v_pk_mul_f32 v[68:69], v[68:69], v[152:153] op_sel:[0,1]
	v_pk_mul_f32 v[70:71], v[70:71], v[152:153] op_sel:[0,1]
	v_pk_mul_f32 v[56:57], v[56:57], v[160:161] op_sel_hi:[1,0]
	v_pk_mul_f32 v[58:59], v[58:59], v[160:161] op_sel_hi:[1,0]
	v_pk_mul_f32 v[52:53], v[52:53], v[160:161] op_sel:[0,1]
	v_pk_mul_f32 v[54:55], v[54:55], v[160:161] op_sel:[0,1]
	v_pk_mul_f32 v[40:41], v[40:41], v[160:161] op_sel_hi:[1,0]
	v_pk_mul_f32 v[42:43], v[42:43], v[160:161] op_sel_hi:[1,0]
	v_pk_mul_f32 v[36:37], v[36:37], v[160:161] op_sel:[0,1]
	v_pk_mul_f32 v[38:39], v[38:39], v[160:161] op_sel:[0,1]
	v_pk_mul_f32 v[24:25], v[24:25], v[160:161] op_sel_hi:[1,0]
	v_pk_mul_f32 v[26:27], v[26:27], v[160:161] op_sel_hi:[1,0]
	v_pk_mul_f32 v[20:21], v[20:21], v[160:161] op_sel:[0,1]
	v_pk_mul_f32 v[22:23], v[22:23], v[160:161] op_sel:[0,1]
	v_pk_mul_f32 v[8:9], v[8:9], v[160:161] op_sel_hi:[1,0]
	v_pk_mul_f32 v[10:11], v[10:11], v[160:161] op_sel_hi:[1,0]
	v_pk_mul_f32 v[4:5], v[4:5], v[160:161] op_sel:[0,1]
	v_pk_mul_f32 v[6:7], v[6:7], v[160:161] op_sel:[0,1]
	s_and_saveexec_b64 s[52:53], s[56:57]
	ds_write_b128 v155, v[120:123] offset:0
	ds_write_b128 v155, v[116:119] offset:256
	ds_write_b128 v155, v[88:91] offset:64
	ds_write_b128 v155, v[84:87] offset:320
	ds_write_b128 v155, v[104:107] offset:128
	ds_write_b128 v155, v[100:103] offset:384
	ds_write_b128 v155, v[72:75] offset:192
	ds_write_b128 v155, v[68:71] offset:448
	ds_write_b128 v155, v[56:59] offset:4096
	ds_write_b128 v155, v[52:55] offset:4352
	ds_write_b128 v155, v[24:27] offset:4160
	ds_write_b128 v155, v[20:23] offset:4416
	ds_write_b128 v155, v[40:43] offset:4224
	ds_write_b128 v155, v[36:39] offset:4480
	ds_write_b128 v155, v[8:11] offset:4288
	ds_write_b128 v155, v[4:7] offset:4544
	s_mov_b64 exec, s[52:53]
	v_pk_mul_f32 v[128:129], v[128:129], v[150:151] op_sel_hi:[1,0]
	v_pk_mul_f32 v[130:131], v[130:131], v[150:151] op_sel_hi:[1,0]
	v_pk_mul_f32 v[124:125], v[124:125], v[150:151] op_sel:[0,1]
	v_pk_mul_f32 v[126:127], v[126:127], v[150:151] op_sel:[0,1]
	v_pk_mul_f32 v[112:113], v[112:113], v[150:151] op_sel_hi:[1,0]
	v_pk_mul_f32 v[114:115], v[114:115], v[150:151] op_sel_hi:[1,0]
	v_pk_mul_f32 v[108:109], v[108:109], v[150:151] op_sel:[0,1]
	v_pk_mul_f32 v[110:111], v[110:111], v[150:151] op_sel:[0,1]
	v_pk_mul_f32 v[96:97], v[96:97], v[150:151] op_sel_hi:[1,0]
	v_pk_mul_f32 v[98:99], v[98:99], v[150:151] op_sel_hi:[1,0]
	v_pk_mul_f32 v[92:93], v[92:93], v[150:151] op_sel:[0,1]
	v_pk_mul_f32 v[94:95], v[94:95], v[150:151] op_sel:[0,1]
	v_pk_mul_f32 v[80:81], v[80:81], v[150:151] op_sel_hi:[1,0]
	v_pk_mul_f32 v[82:83], v[82:83], v[150:151] op_sel_hi:[1,0]
	v_pk_mul_f32 v[76:77], v[76:77], v[150:151] op_sel:[0,1]
	v_pk_mul_f32 v[78:79], v[78:79], v[150:151] op_sel:[0,1]
	v_pk_mul_f32 v[64:65], v[64:65], v[158:159] op_sel_hi:[1,0]
	v_pk_mul_f32 v[66:67], v[66:67], v[158:159] op_sel_hi:[1,0]
	v_pk_mul_f32 v[60:61], v[60:61], v[158:159] op_sel:[0,1]
	v_pk_mul_f32 v[62:63], v[62:63], v[158:159] op_sel:[0,1]
	v_pk_mul_f32 v[48:49], v[48:49], v[158:159] op_sel_hi:[1,0]
	v_pk_mul_f32 v[50:51], v[50:51], v[158:159] op_sel_hi:[1,0]
	v_pk_mul_f32 v[44:45], v[44:45], v[158:159] op_sel:[0,1]
	v_pk_mul_f32 v[46:47], v[46:47], v[158:159] op_sel:[0,1]
	v_pk_mul_f32 v[32:33], v[32:33], v[158:159] op_sel_hi:[1,0]
	v_pk_mul_f32 v[34:35], v[34:35], v[158:159] op_sel_hi:[1,0]
	v_pk_mul_f32 v[28:29], v[28:29], v[158:159] op_sel:[0,1]
	v_pk_mul_f32 v[30:31], v[30:31], v[158:159] op_sel:[0,1]
	v_pk_mul_f32 v[16:17], v[16:17], v[158:159] op_sel_hi:[1,0]
	v_pk_mul_f32 v[18:19], v[18:19], v[158:159] op_sel_hi:[1,0]
	v_pk_mul_f32 v[12:13], v[12:13], v[158:159] op_sel:[0,1]
	v_pk_mul_f32 v[14:15], v[14:15], v[158:159] op_sel:[0,1]
	s_waitcnt lgkmcnt(0)
	s_barrier
	ds_read_b128 v[134:137], v204 offset:0
	ds_read_b128 v[138:141], v204 offset:1024
	ds_read_b128 v[142:145], v204 offset:2048
	ds_read_b128 v[146:149], v204 offset:3072
	ds_read_b128 v[222:225], v205 offset:0
	ds_read_b128 v[226:229], v205 offset:256
	ds_read_b128 v[230:233], v205 offset:4096
	ds_read_b128 v[234:237], v205 offset:4352
	ds_read_b128 v[184:187], v204 offset:512
	ds_read_b128 v[188:191], v204 offset:1536
	ds_read_b128 v[192:195], v204 offset:2560
	ds_read_b128 v[196:199], v204 offset:3584
	s_waitcnt lgkmcnt(6)
	s_and_b64 vcc, exec, s[28:29]
	s_cbranch_vccz .Lup_z000
	v_mov_b32_dpp v226, v116 row_shr:1 row_mask:0xf bank_mask:0xf
	v_mov_b32_dpp v227, v117 row_shr:1 row_mask:0xf bank_mask:0xf
	v_mov_b32_dpp v228, v118 row_shr:1 row_mask:0xf bank_mask:0xf
	v_mov_b32_dpp v229, v119 row_shr:1 row_mask:0xf bank_mask:0xf
	v_mov_b32_dpp v222, v120 row_shr:1 row_mask:0xf bank_mask:0xf
	v_mov_b32_dpp v223, v121 row_shr:1 row_mask:0xf bank_mask:0xf
	v_mov_b32_dpp v224, v122 row_shr:1 row_mask:0xf bank_mask:0xf
	v_mov_b32_dpp v225, v123 row_shr:1 row_mask:0xf bank_mask:0xf
	s_branch .Lup_d000
.Lup_z000:
	v_mov_b32_dpp v226, v116 row_shr:1 row_mask:0xf bank_mask:0xf bound_ctrl:1
	v_mov_b32_dpp v227, v117 row_shr:1 row_mask:0xf bank_mask:0xf bound_ctrl:1
	v_mov_b32_dpp v228, v118 row_shr:1 row_mask:0xf bank_mask:0xf bound_ctrl:1
	v_mov_b32_dpp v229, v119 row_shr:1 row_mask:0xf bank_mask:0xf bound_ctrl:1
	v_mov_b32_dpp v222, v120 row_shr:1 row_mask:0xf bank_mask:0xf bound_ctrl:1
	v_mov_b32_dpp v223, v121 row_shr:1 row_mask:0xf bank_mask:0xf bound_ctrl:1
	v_mov_b32_dpp v224, v122 row_shr:1 row_mask:0xf bank_mask:0xf bound_ctrl:1
	v_mov_b32_dpp v225, v123 row_shr:1 row_mask:0xf bank_mask:0xf bound_ctrl:1
.Lup_d000:
	v_pk_fma_f32 v[116:117], v[116:117], v[142:143], v[146:147]
	v_pk_fma_f32 v[118:119], v[118:119], v[144:145], v[148:149]
	v_pk_fma_f32 v[116:117], v[120:121], v[138:139], v[116:117]
	v_pk_fma_f32 v[118:119], v[122:123], v[140:141], v[118:119]
	v_pk_fma_f32 v[116:117], v[124:125], v[134:135], v[116:117]
	v_pk_fma_f32 v[118:119], v[126:127], v[136:137], v[118:119]
	v_pk_fma_f32 v[120:121], v[120:121], v[142:143], v[146:147]
	v_pk_fma_f32 v[122:123], v[122:123], v[144:145], v[148:149]
	v_pk_fma_f32 v[120:121], v[124:125], v[138:139], v[120:121]
	v_pk_fma_f32 v[122:123], v[126:127], v[140:141], v[122:123]
	v_pk_fma_f32 v[120:121], v[128:129], v[134:135], v[120:121]
	v_pk_fma_f32 v[122:123], v[130:131], v[136:137], v[122:123]
	v_pk_fma_f32 v[124:125], v[124:125], v[142:143], v[146:147]
	v_pk_fma_f32 v[126:127], v[126:127], v[144:145], v[148:149]
	v_pk_fma_f32 v[124:125], v[128:129], v[138:139], v[124:125]
	v_pk_fma_f32 v[126:127], v[130:131], v[140:141], v[126:127]
	v_pk_fma_f32 v[124:125], v[226:227], v[134:135], v[124:125]
	v_pk_fma_f32 v[126:127], v[228:229], v[136:137], v[126:127]
	v_pk_fma_f32 v[128:129], v[128:129], v[142:143], v[146:147]
	v_pk_fma_f32 v[130:131], v[130:131], v[144:145], v[148:149]
	v_pk_fma_f32 v[128:129], v[226:227], v[138:139], v[128:129]
	v_pk_fma_f32 v[130:131], v[228:229], v[140:141], v[130:131]
	v_pk_fma_f32 v[128:129], v[222:223], v[134:135], v[128:129]
	v_pk_fma_f32 v[130:131], v[224:225], v[136:137], v[130:131]
	s_and_b64 vcc, exec, s[28:29]
	s_cbranch_vccnz .Lup_nohp000
	s_add_u32 s48, s22, s41
	s_addc_u32 s49, s23, 0
	s_add_u32 s16, s48, 0x5800
	s_addc_u32 s17, s49, 0
	v_cmp_eq_u32_e32 vcc, 0, v157
	s_and_saveexec_b64 s[52:53], vcc
	global_store_dwordx4 v3, v[128:131], s[48:49] offset:0
	global_store_dwordx4 v3, v[124:127], s[16:17] offset:0
	s_mov_b64 exec, s[52:53]
	s_nop 4
.Lup_nohp000:
	ds_read_b128 v[222:225], v205 offset:128
	ds_read_b128 v[226:229], v205 offset:384
	s_waitcnt lgkmcnt(6)
	v_mov_b32_dpp v234, v52 row_shr:1 row_mask:0xf bank_mask:0xf
	v_mov_b32_dpp v235, v53 row_shr:1 row_mask:0xf bank_mask:0xf
	v_mov_b32_dpp v236, v54 row_shr:1 row_mask:0xf bank_mask:0xf
	v_mov_b32_dpp v237, v55 row_shr:1 row_mask:0xf bank_mask:0xf
	v_mov_b32_dpp v230, v56 row_shr:1 row_mask:0xf bank_mask:0xf
	v_mov_b32_dpp v231, v57 row_shr:1 row_mask:0xf bank_mask:0xf
	v_mov_b32_dpp v232, v58 row_shr:1 row_mask:0xf bank_mask:0xf
	v_mov_b32_dpp v233, v59 row_shr:1 row_mask:0xf bank_mask:0xf
	s_and_b64 vcc, exec, s[28:29]
	s_cbranch_vccz .Lup_nohc001
	v_pk_mul_f32 v[200:201], v[134:135], v[52:53]
	v_pk_mul_f32 v[202:203], v[136:137], v[54:55]
	v_pk_mul_f32 v[238:239], v[134:135], v[56:57]
	v_pk_mul_f32 v[240:241], v[136:137], v[58:59]
	v_pk_fma_f32 v[238:239], v[138:139], v[52:53], v[238:239]
	v_pk_fma_f32 v[240:241], v[140:141], v[54:55], v[240:241]
	s_add_u32 s48, s24, s41
	s_addc_u32 s49, s25, 0
	s_add_u32 s16, s48, 0x5800
	s_addc_u32 s17, s49, 0
	s_and_saveexec_b64 s[52:53], s[56:57]
	global_store_dwordx4 v3, v[200:203], s[48:49] offset:0
	global_store_dwordx4 v3, v[238:241], s[16:17] offset:0
	s_mov_b64 exec, s[52:53]
.Lup_nohc001:
	v_pk_fma_f32 v[52:53], v[52:53], v[142:143], v[146:147]
	v_pk_fma_f32 v[54:55], v[54:55], v[144:145], v[148:149]
	v_pk_fma_f32 v[52:53], v[56:57], v[138:139], v[52:53]
	v_pk_fma_f32 v[54:55], v[58:59], v[140:141], v[54:55]
	v_pk_fma_f32 v[52:53], v[60:61], v[134:135], v[52:53]
	v_pk_fma_f32 v[54:55], v[62:63], v[136:137], v[54:55]
	v_pk_fma_f32 v[56:57], v[56:57], v[142:143], v[146:147]
	v_pk_fma_f32 v[58:59], v[58:59], v[144:145], v[148:149]
	v_pk_fma_f32 v[56:57], v[60:61], v[138:139], v[56:57]
	v_pk_fma_f32 v[58:59], v[62:63], v[140:141], v[58:59]
	v_pk_fma_f32 v[56:57], v[64:65], v[134:135], v[56:57]
	v_pk_fma_f32 v[58:59], v[66:67], v[136:137], v[58:59]
	v_pk_fma_f32 v[60:61], v[60:61], v[142:143], v[146:147]
	v_pk_fma_f32 v[62:63], v[62:63], v[144:145], v[148:149]
	v_pk_fma_f32 v[60:61], v[64:65], v[138:139], v[60:61]
	v_pk_fma_f32 v[62:63], v[66:67], v[140:141], v[62:63]
	v_pk_fma_f32 v[60:61], v[234:235], v[134:135], v[60:61]
	v_pk_fma_f32 v[62:63], v[236:237], v[136:137], v[62:63]
	v_pk_fma_f32 v[64:65], v[64:65], v[142:143], v[146:147]
	v_pk_fma_f32 v[66:67], v[66:67], v[144:145], v[148:149]
	v_pk_fma_f32 v[64:65], v[234:235], v[138:139], v[64:65]
	v_pk_fma_f32 v[66:67], v[236:237], v[140:141], v[66:67]
	v_pk_fma_f32 v[64:65], v[230:231], v[134:135], v[64:65]
	v_pk_fma_f32 v[66:67], v[232:233], v[136:137], v[66:67]
	ds_read_b128 v[230:233], v205 offset:4224
	ds_read_b128 v[234:237], v205 offset:4480
	ds_read_b128 v[134:137], v204 offset:16
	ds_read_b128 v[138:141], v204 offset:1040
	ds_read_b128 v[142:145], v204 offset:2064
	ds_read_b128 v[146:149], v204 offset:3088
	s_waitcnt lgkmcnt(6)
	s_and_b64 vcc, exec, s[28:29]
	s_cbranch_vccz .Lup_z010
	v_mov_b32_dpp v226, v100 row_shr:1 row_mask:0xf bank_mask:0xf
	v_mov_b32_dpp v227, v101 row_shr:1 row_mask:0xf bank_mask:0xf
	v_mov_b32_dpp v228, v102 row_shr:1 row_mask:0xf bank_mask:0xf
	v_mov_b32_dpp v229, v103 row_shr:1 row_mask:0xf bank_mask:0xf
	v_mov_b32_dpp v222, v104 row_shr:1 row_mask:0xf bank_mask:0xf
	v_mov_b32_dpp v223, v105 row_shr:1 row_mask:0xf bank_mask:0xf
	v_mov_b32_dpp v224, v106 row_shr:1 row_mask:0xf bank_mask:0xf
	v_mov_b32_dpp v225, v107 row_shr:1 row_mask:0xf bank_mask:0xf
	s_branch .Lup_d010
.Lup_z010:
	v_mov_b32_dpp v226, v100 row_shr:1 row_mask:0xf bank_mask:0xf bound_ctrl:1
	v_mov_b32_dpp v227, v101 row_shr:1 row_mask:0xf bank_mask:0xf bound_ctrl:1
	v_mov_b32_dpp v228, v102 row_shr:1 row_mask:0xf bank_mask:0xf bound_ctrl:1
	v_mov_b32_dpp v229, v103 row_shr:1 row_mask:0xf bank_mask:0xf bound_ctrl:1
	v_mov_b32_dpp v222, v104 row_shr:1 row_mask:0xf bank_mask:0xf bound_ctrl:1
	v_mov_b32_dpp v223, v105 row_shr:1 row_mask:0xf bank_mask:0xf bound_ctrl:1
	v_mov_b32_dpp v224, v106 row_shr:1 row_mask:0xf bank_mask:0xf bound_ctrl:1
	v_mov_b32_dpp v225, v107 row_shr:1 row_mask:0xf bank_mask:0xf bound_ctrl:1
.Lup_d010:
	v_pk_fma_f32 v[100:101], v[100:101], v[192:193], v[196:197]
	v_pk_fma_f32 v[102:103], v[102:103], v[194:195], v[198:199]
	v_pk_fma_f32 v[100:101], v[104:105], v[188:189], v[100:101]
	v_pk_fma_f32 v[102:103], v[106:107], v[190:191], v[102:103]
	v_pk_fma_f32 v[100:101], v[108:109], v[184:185], v[100:101]
	v_pk_fma_f32 v[102:103], v[110:111], v[186:187], v[102:103]
	v_pk_fma_f32 v[104:105], v[104:105], v[192:193], v[196:197]
	v_pk_fma_f32 v[106:107], v[106:107], v[194:195], v[198:199]
	v_pk_fma_f32 v[104:105], v[108:109], v[188:189], v[104:105]
	v_pk_fma_f32 v[106:107], v[110:111], v[190:191], v[106:107]
	v_pk_fma_f32 v[104:105], v[112:113], v[184:185], v[104:105]
	v_pk_fma_f32 v[106:107], v[114:115], v[186:187], v[106:107]
	v_pk_fma_f32 v[108:109], v[108:109], v[192:193], v[196:197]
	v_pk_fma_f32 v[110:111], v[110:111], v[194:195], v[198:199]
	v_pk_fma_f32 v[108:109], v[112:113], v[188:189], v[108:109]
	v_pk_fma_f32 v[110:111], v[114:115], v[190:191], v[110:111]
	v_pk_fma_f32 v[108:109], v[226:227], v[184:185], v[108:109]
	v_pk_fma_f32 v[110:111], v[228:229], v[186:187], v[110:111]
	v_pk_fma_f32 v[112:113], v[112:113], v[192:193], v[196:197]
	v_pk_fma_f32 v[114:115], v[114:115], v[194:195], v[198:199]
	v_pk_fma_f32 v[112:113], v[226:227], v[188:189], v[112:113]
	v_pk_fma_f32 v[114:115], v[228:229], v[190:191], v[114:115]
	v_pk_fma_f32 v[112:113], v[222:223], v[184:185], v[112:113]
	v_pk_fma_f32 v[114:115], v[224:225], v[186:187], v[114:115]
	s_and_b64 vcc, exec, s[28:29]
	s_cbranch_vccnz .Lup_nohp010
	s_add_u32 s48, s22, s41
	s_addc_u32 s49, s23, 0
	s_add_u32 s16, s48, 0x5800
	s_addc_u32 s17, s49, 0
	v_cmp_eq_u32_e32 vcc, 0, v157
	s_and_saveexec_b64 s[52:53], vcc
	global_store_dwordx4 v3, v[112:115], s[48:49] offset:512
	global_store_dwordx4 v3, v[108:111], s[16:17] offset:512
	s_mov_b64 exec, s[52:53]
	s_nop 4
.Lup_nohp010:
	ds_read_b128 v[222:225], v205 offset:64
	ds_read_b128 v[226:229], v205 offset:320
	v_pk_mul_f32 v[150:151], v[128:129], s[10:11]
	v_pk_mul_f32 v[152:153], v[130:131], s[10:11]
	v_pk_mul_f32 v[158:159], v[124:125], s[10:11]
	v_pk_mul_f32 v[160:161], v[126:127], s[10:11]
	v_exp_f32_e32 v150, v150
	v_exp_f32_e32 v151, v151
	v_exp_f32_e32 v152, v152
	v_exp_f32_e32 v153, v153
	v_exp_f32_e32 v158, v158
	v_exp_f32_e32 v159, v159
	v_exp_f32_e32 v160, v160
	v_exp_f32_e32 v161, v161
	v_pk_add_f32 v[150:151], v[150:151], s[12:13]
	v_pk_add_f32 v[152:153], v[152:153], s[12:13]
	v_pk_add_f32 v[158:159], v[158:159], s[12:13]
	v_pk_add_f32 v[160:161], v[160:161], s[12:13]
	v_rcp_f32_e32 v150, v150
	v_rcp_f32_e32 v151, v151
	v_rcp_f32_e32 v152, v152
	v_rcp_f32_e32 v153, v153
	v_rcp_f32_e32 v158, v158
	v_rcp_f32_e32 v159, v159
	v_rcp_f32_e32 v160, v160
	v_rcp_f32_e32 v161, v161
	v_pk_mul_f32 v[150:151], v[128:129], v[150:151]
	v_pk_mul_f32 v[152:153], v[130:131], v[152:153]
	v_pk_mul_f32 v[158:159], v[124:125], v[158:159]
	v_pk_mul_f32 v[160:161], v[126:127], v[160:161]
	v_pk_mul_f32 v[150:151], v[150:151], v[112:113]
	v_pk_mul_f32 v[152:153], v[152:153], v[114:115]
	v_pk_mul_f32 v[158:159], v[158:159], v[108:109]
	v_pk_mul_f32 v[160:161], v[160:161], v[110:111]
	v_cvt_pk_bf16_f32 v128, v150, v151
	v_cvt_pk_bf16_f32 v129, v152, v153
	v_cvt_pk_bf16_f32 v124, v158, v159
	v_cvt_pk_bf16_f32 v125, v160, v161
	v_pk_mul_f32 v[150:151], v[120:121], s[10:11]
	v_pk_mul_f32 v[152:153], v[122:123], s[10:11]
	v_pk_mul_f32 v[158:159], v[116:117], s[10:11]
	v_pk_mul_f32 v[160:161], v[118:119], s[10:11]
	v_exp_f32_e32 v150, v150
	v_exp_f32_e32 v151, v151
	v_exp_f32_e32 v152, v152
	v_exp_f32_e32 v153, v153
	v_exp_f32_e32 v158, v158
	v_exp_f32_e32 v159, v159
	v_exp_f32_e32 v160, v160
	v_exp_f32_e32 v161, v161
	v_pk_add_f32 v[150:151], v[150:151], s[12:13]
	v_pk_add_f32 v[152:153], v[152:153], s[12:13]
	v_pk_add_f32 v[158:159], v[158:159], s[12:13]
	v_pk_add_f32 v[160:161], v[160:161], s[12:13]
	v_rcp_f32_e32 v150, v150
	v_rcp_f32_e32 v151, v151
	v_rcp_f32_e32 v152, v152
	v_rcp_f32_e32 v153, v153
	v_rcp_f32_e32 v158, v158
	v_rcp_f32_e32 v159, v159
	v_rcp_f32_e32 v160, v160
	v_rcp_f32_e32 v161, v161
	v_pk_mul_f32 v[150:151], v[120:121], v[150:151]
	v_pk_mul_f32 v[152:153], v[122:123], v[152:153]
	v_pk_mul_f32 v[158:159], v[116:117], v[158:159]
	v_pk_mul_f32 v[160:161], v[118:119], v[160:161]
	v_pk_mul_f32 v[150:151], v[150:151], v[104:105]
	v_pk_mul_f32 v[152:153], v[152:153], v[106:107]
	v_pk_mul_f32 v[158:159], v[158:159], v[100:101]
	v_pk_mul_f32 v[160:161], v[160:161], v[102:103]
	v_cvt_pk_bf16_f32 v120, v150, v151
	v_cvt_pk_bf16_f32 v121, v152, v153
	v_cvt_pk_bf16_f32 v116, v158, v159
	v_cvt_pk_bf16_f32 v117, v160, v161
	s_waitcnt lgkmcnt(6)
	v_mov_b32_dpp v234, v36 row_shr:1 row_mask:0xf bank_mask:0xf
	v_mov_b32_dpp v235, v37 row_shr:1 row_mask:0xf bank_mask:0xf
	v_mov_b32_dpp v236, v38 row_shr:1 row_mask:0xf bank_mask:0xf
	v_mov_b32_dpp v237, v39 row_shr:1 row_mask:0xf bank_mask:0xf
	v_mov_b32_dpp v230, v40 row_shr:1 row_mask:0xf bank_mask:0xf
	v_mov_b32_dpp v231, v41 row_shr:1 row_mask:0xf bank_mask:0xf
	v_mov_b32_dpp v232, v42 row_shr:1 row_mask:0xf bank_mask:0xf
	v_mov_b32_dpp v233, v43 row_shr:1 row_mask:0xf bank_mask:0xf
	s_and_b64 vcc, exec, s[28:29]
	s_cbranch_vccz .Lup_nohc011
	v_pk_mul_f32 v[200:201], v[184:185], v[36:37]
	v_pk_mul_f32 v[202:203], v[186:187], v[38:39]
	v_pk_mul_f32 v[238:239], v[184:185], v[40:41]
	v_pk_mul_f32 v[240:241], v[186:187], v[42:43]
	v_pk_fma_f32 v[238:239], v[188:189], v[36:37], v[238:239]
	v_pk_fma_f32 v[240:241], v[190:191], v[38:39], v[240:241]
	s_add_u32 s48, s24, s41
	s_addc_u32 s49, s25, 0
	s_add_u32 s16, s48, 0x5800
	s_addc_u32 s17, s49, 0
	s_and_saveexec_b64 s[52:53], s[56:57]
	global_store_dwordx4 v3, v[200:203], s[48:49] offset:512
	global_store_dwordx4 v3, v[238:241], s[16:17] offset:512
	s_mov_b64 exec, s[52:53]
.Lup_nohc011:
	v_pk_fma_f32 v[36:37], v[36:37], v[192:193], v[196:197]
	v_pk_fma_f32 v[38:39], v[38:39], v[194:195], v[198:199]
	v_pk_fma_f32 v[36:37], v[40:41], v[188:189], v[36:37]
	v_pk_fma_f32 v[38:39], v[42:43], v[190:191], v[38:39]
	v_pk_fma_f32 v[36:37], v[44:45], v[184:185], v[36:37]
	v_pk_fma_f32 v[38:39], v[46:47], v[186:187], v[38:39]
	v_pk_fma_f32 v[40:41], v[40:41], v[192:193], v[196:197]
	v_pk_fma_f32 v[42:43], v[42:43], v[194:195], v[198:199]
	v_pk_fma_f32 v[40:41], v[44:45], v[188:189], v[40:41]
	v_pk_fma_f32 v[42:43], v[46:47], v[190:191], v[42:43]
	v_pk_fma_f32 v[40:41], v[48:49], v[184:185], v[40:41]
	v_pk_fma_f32 v[42:43], v[50:51], v[186:187], v[42:43]
	v_pk_fma_f32 v[44:45], v[44:45], v[192:193], v[196:197]
	v_pk_fma_f32 v[46:47], v[46:47], v[194:195], v[198:199]
	v_pk_fma_f32 v[44:45], v[48:49], v[188:189], v[44:45]
	v_pk_fma_f32 v[46:47], v[50:51], v[190:191], v[46:47]
	v_pk_fma_f32 v[44:45], v[234:235], v[184:185], v[44:45]
	v_pk_fma_f32 v[46:47], v[236:237], v[186:187], v[46:47]
	v_pk_fma_f32 v[48:49], v[48:49], v[192:193], v[196:197]
	v_pk_fma_f32 v[50:51], v[50:51], v[194:195], v[198:199]
	v_pk_fma_f32 v[48:49], v[234:235], v[188:189], v[48:49]
	v_pk_fma_f32 v[50:51], v[236:237], v[190:191], v[50:51]
	v_pk_fma_f32 v[48:49], v[230:231], v[184:185], v[48:49]
	v_pk_fma_f32 v[50:51], v[232:233], v[186:187], v[50:51]
	ds_read_b128 v[230:233], v205 offset:4160
	ds_read_b128 v[234:237], v205 offset:4416
	ds_read_b128 v[184:187], v204 offset:528
	ds_read_b128 v[188:191], v204 offset:1552
	ds_read_b128 v[192:195], v204 offset:2576
	ds_read_b128 v[196:199], v204 offset:3600
	v_pk_mul_f32 v[150:151], v[64:65], s[10:11]
	v_pk_mul_f32 v[152:153], v[66:67], s[10:11]
	v_pk_mul_f32 v[158:159], v[60:61], s[10:11]
	v_pk_mul_f32 v[160:161], v[62:63], s[10:11]
	v_exp_f32_e32 v150, v150
	v_exp_f32_e32 v151, v151
	v_exp_f32_e32 v152, v152
	v_exp_f32_e32 v153, v153
	v_exp_f32_e32 v158, v158
	v_exp_f32_e32 v159, v159
	v_exp_f32_e32 v160, v160
	v_exp_f32_e32 v161, v161
	v_pk_add_f32 v[150:151], v[150:151], s[12:13]
	v_pk_add_f32 v[152:153], v[152:153], s[12:13]
	v_pk_add_f32 v[158:159], v[158:159], s[12:13]
	v_pk_add_f32 v[160:161], v[160:161], s[12:13]
	v_rcp_f32_e32 v150, v150
	v_rcp_f32_e32 v151, v151
	v_rcp_f32_e32 v152, v152
	v_rcp_f32_e32 v153, v153
	v_rcp_f32_e32 v158, v158
	v_rcp_f32_e32 v159, v159
	v_rcp_f32_e32 v160, v160
	v_rcp_f32_e32 v161, v161
	v_pk_mul_f32 v[150:151], v[64:65], v[150:151]
	v_pk_mul_f32 v[152:153], v[66:67], v[152:153]
	v_pk_mul_f32 v[158:159], v[60:61], v[158:159]
	v_pk_mul_f32 v[160:161], v[62:63], v[160:161]
	v_pk_mul_f32 v[150:151], v[150:151], v[48:49]
	v_pk_mul_f32 v[152:153], v[152:153], v[50:51]
	v_pk_mul_f32 v[158:159], v[158:159], v[44:45]
	v_pk_mul_f32 v[160:161], v[160:161], v[46:47]
	v_cvt_pk_bf16_f32 v64, v150, v151
	v_cvt_pk_bf16_f32 v65, v152, v153
	v_cvt_pk_bf16_f32 v60, v158, v159
	v_cvt_pk_bf16_f32 v61, v160, v161
	v_pk_mul_f32 v[150:151], v[56:57], s[10:11]
	v_pk_mul_f32 v[152:153], v[58:59], s[10:11]
	v_pk_mul_f32 v[158:159], v[52:53], s[10:11]
	v_pk_mul_f32 v[160:161], v[54:55], s[10:11]
	v_exp_f32_e32 v150, v150
	v_exp_f32_e32 v151, v151
	v_exp_f32_e32 v152, v152
	v_exp_f32_e32 v153, v153
	v_exp_f32_e32 v158, v158
	v_exp_f32_e32 v159, v159
	v_exp_f32_e32 v160, v160
	v_exp_f32_e32 v161, v161
	v_pk_add_f32 v[150:151], v[150:151], s[12:13]
	v_pk_add_f32 v[152:153], v[152:153], s[12:13]
	v_pk_add_f32 v[158:159], v[158:159], s[12:13]
	v_pk_add_f32 v[160:161], v[160:161], s[12:13]
	v_rcp_f32_e32 v150, v150
	v_rcp_f32_e32 v151, v151
	v_rcp_f32_e32 v152, v152
	v_rcp_f32_e32 v153, v153
	v_rcp_f32_e32 v158, v158
	v_rcp_f32_e32 v159, v159
	v_rcp_f32_e32 v160, v160
	v_rcp_f32_e32 v161, v161
	v_pk_mul_f32 v[150:151], v[56:57], v[150:151]
	v_pk_mul_f32 v[152:153], v[58:59], v[152:153]
	v_pk_mul_f32 v[158:159], v[52:53], v[158:159]
	v_pk_mul_f32 v[160:161], v[54:55], v[160:161]
	v_pk_mul_f32 v[150:151], v[150:151], v[40:41]
	v_pk_mul_f32 v[152:153], v[152:153], v[42:43]
	v_pk_mul_f32 v[158:159], v[158:159], v[36:37]
	v_pk_mul_f32 v[160:161], v[160:161], v[38:39]
	v_cvt_pk_bf16_f32 v56, v150, v151
	v_cvt_pk_bf16_f32 v57, v152, v153
	v_cvt_pk_bf16_f32 v52, v158, v159
	v_cvt_pk_bf16_f32 v53, v160, v161
	s_waitcnt lgkmcnt(6)
	s_and_b64 vcc, exec, s[28:29]
	s_cbranch_vccz .Lup_z100
	v_mov_b32_dpp v226, v84 row_shr:1 row_mask:0xf bank_mask:0xf
	v_mov_b32_dpp v227, v85 row_shr:1 row_mask:0xf bank_mask:0xf
	v_mov_b32_dpp v228, v86 row_shr:1 row_mask:0xf bank_mask:0xf
	v_mov_b32_dpp v229, v87 row_shr:1 row_mask:0xf bank_mask:0xf
	v_mov_b32_dpp v222, v88 row_shr:1 row_mask:0xf bank_mask:0xf
	v_mov_b32_dpp v223, v89 row_shr:1 row_mask:0xf bank_mask:0xf
	v_mov_b32_dpp v224, v90 row_shr:1 row_mask:0xf bank_mask:0xf
	v_mov_b32_dpp v225, v91 row_shr:1 row_mask:0xf bank_mask:0xf
	s_branch .Lup_d100
.Lup_z100:
	v_mov_b32_dpp v226, v84 row_shr:1 row_mask:0xf bank_mask:0xf bound_ctrl:1
	v_mov_b32_dpp v227, v85 row_shr:1 row_mask:0xf bank_mask:0xf bound_ctrl:1
	v_mov_b32_dpp v228, v86 row_shr:1 row_mask:0xf bank_mask:0xf bound_ctrl:1
	v_mov_b32_dpp v229, v87 row_shr:1 row_mask:0xf bank_mask:0xf bound_ctrl:1
	v_mov_b32_dpp v222, v88 row_shr:1 row_mask:0xf bank_mask:0xf bound_ctrl:1
	v_mov_b32_dpp v223, v89 row_shr:1 row_mask:0xf bank_mask:0xf bound_ctrl:1
	v_mov_b32_dpp v224, v90 row_shr:1 row_mask:0xf bank_mask:0xf bound_ctrl:1
	v_mov_b32_dpp v225, v91 row_shr:1 row_mask:0xf bank_mask:0xf bound_ctrl:1
.Lup_d100:
	v_pk_fma_f32 v[84:85], v[84:85], v[142:143], v[146:147]
	v_pk_fma_f32 v[86:87], v[86:87], v[144:145], v[148:149]
	v_pk_fma_f32 v[84:85], v[88:89], v[138:139], v[84:85]
	v_pk_fma_f32 v[86:87], v[90:91], v[140:141], v[86:87]
	v_pk_fma_f32 v[84:85], v[92:93], v[134:135], v[84:85]
	v_pk_fma_f32 v[86:87], v[94:95], v[136:137], v[86:87]
	v_pk_fma_f32 v[88:89], v[88:89], v[142:143], v[146:147]
	v_pk_fma_f32 v[90:91], v[90:91], v[144:145], v[148:149]
	v_pk_fma_f32 v[88:89], v[92:93], v[138:139], v[88:89]
	v_pk_fma_f32 v[90:91], v[94:95], v[140:141], v[90:91]
	v_pk_fma_f32 v[88:89], v[96:97], v[134:135], v[88:89]
	v_pk_fma_f32 v[90:91], v[98:99], v[136:137], v[90:91]
	v_pk_fma_f32 v[92:93], v[92:93], v[142:143], v[146:147]
	v_pk_fma_f32 v[94:95], v[94:95], v[144:145], v[148:149]
	v_pk_fma_f32 v[92:93], v[96:97], v[138:139], v[92:93]
	v_pk_fma_f32 v[94:95], v[98:99], v[140:141], v[94:95]
	v_pk_fma_f32 v[92:93], v[226:227], v[134:135], v[92:93]
	v_pk_fma_f32 v[94:95], v[228:229], v[136:137], v[94:95]
	v_pk_fma_f32 v[96:97], v[96:97], v[142:143], v[146:147]
	v_pk_fma_f32 v[98:99], v[98:99], v[144:145], v[148:149]
	v_pk_fma_f32 v[96:97], v[226:227], v[138:139], v[96:97]
	v_pk_fma_f32 v[98:99], v[228:229], v[140:141], v[98:99]
	v_pk_fma_f32 v[96:97], v[222:223], v[134:135], v[96:97]
	v_pk_fma_f32 v[98:99], v[224:225], v[136:137], v[98:99]
	s_and_b64 vcc, exec, s[28:29]
	s_cbranch_vccnz .Lup_nohp100
	s_add_u32 s48, s22, s41
	s_addc_u32 s49, s23, 0
	s_add_u32 s16, s48, 0x5800
	s_addc_u32 s17, s49, 0
	v_cmp_eq_u32_e32 vcc, 0, v157
	s_and_saveexec_b64 s[52:53], vcc
	global_store_dwordx4 v3, v[96:99], s[48:49] offset:16
	global_store_dwordx4 v3, v[92:95], s[16:17] offset:16
	s_mov_b64 exec, s[52:53]
	s_nop 4
.Lup_nohp100:
	ds_read_b128 v[222:225], v205 offset:192
	ds_read_b128 v[226:229], v205 offset:448
	s_waitcnt lgkmcnt(6)
	v_mov_b32_dpp v234, v20 row_shr:1 row_mask:0xf bank_mask:0xf
	v_mov_b32_dpp v235, v21 row_shr:1 row_mask:0xf bank_mask:0xf
	v_mov_b32_dpp v236, v22 row_shr:1 row_mask:0xf bank_mask:0xf
	v_mov_b32_dpp v237, v23 row_shr:1 row_mask:0xf bank_mask:0xf
	v_mov_b32_dpp v230, v24 row_shr:1 row_mask:0xf bank_mask:0xf
	v_mov_b32_dpp v231, v25 row_shr:1 row_mask:0xf bank_mask:0xf
	v_mov_b32_dpp v232, v26 row_shr:1 row_mask:0xf bank_mask:0xf
	v_mov_b32_dpp v233, v27 row_shr:1 row_mask:0xf bank_mask:0xf
	s_and_b64 vcc, exec, s[28:29]
	s_cbranch_vccz .Lup_nohc101
	v_pk_mul_f32 v[200:201], v[134:135], v[20:21]
	v_pk_mul_f32 v[202:203], v[136:137], v[22:23]
	v_pk_mul_f32 v[238:239], v[134:135], v[24:25]
	v_pk_mul_f32 v[240:241], v[136:137], v[26:27]
	v_pk_fma_f32 v[238:239], v[138:139], v[20:21], v[238:239]
	v_pk_fma_f32 v[240:241], v[140:141], v[22:23], v[240:241]
	s_add_u32 s48, s24, s41
	s_addc_u32 s49, s25, 0
	s_add_u32 s16, s48, 0x5800
	s_addc_u32 s17, s49, 0
	s_and_saveexec_b64 s[52:53], s[56:57]
	global_store_dwordx4 v3, v[200:203], s[48:49] offset:16
	global_store_dwordx4 v3, v[238:241], s[16:17] offset:16
	s_mov_b64 exec, s[52:53]
.Lup_nohc101:
	v_pk_fma_f32 v[20:21], v[20:21], v[142:143], v[146:147]
	v_pk_fma_f32 v[22:23], v[22:23], v[144:145], v[148:149]
	v_pk_fma_f32 v[20:21], v[24:25], v[138:139], v[20:21]
	v_pk_fma_f32 v[22:23], v[26:27], v[140:141], v[22:23]
	v_pk_fma_f32 v[20:21], v[28:29], v[134:135], v[20:21]
	v_pk_fma_f32 v[22:23], v[30:31], v[136:137], v[22:23]
	v_pk_fma_f32 v[24:25], v[24:25], v[142:143], v[146:147]
	v_pk_fma_f32 v[26:27], v[26:27], v[144:145], v[148:149]
	v_pk_fma_f32 v[24:25], v[28:29], v[138:139], v[24:25]
	v_pk_fma_f32 v[26:27], v[30:31], v[140:141], v[26:27]
	v_pk_fma_f32 v[24:25], v[32:33], v[134:135], v[24:25]
	v_pk_fma_f32 v[26:27], v[34:35], v[136:137], v[26:27]
	v_pk_fma_f32 v[28:29], v[28:29], v[142:143], v[146:147]
	v_pk_fma_f32 v[30:31], v[30:31], v[144:145], v[148:149]
	v_pk_fma_f32 v[28:29], v[32:33], v[138:139], v[28:29]
	v_pk_fma_f32 v[30:31], v[34:35], v[140:141], v[30:31]
	v_pk_fma_f32 v[28:29], v[234:235], v[134:135], v[28:29]
	v_pk_fma_f32 v[30:31], v[236:237], v[136:137], v[30:31]
	v_pk_fma_f32 v[32:33], v[32:33], v[142:143], v[146:147]
	v_pk_fma_f32 v[34:35], v[34:35], v[144:145], v[148:149]
	v_pk_fma_f32 v[32:33], v[234:235], v[138:139], v[32:33]
	v_pk_fma_f32 v[34:35], v[236:237], v[140:141], v[34:35]
	v_pk_fma_f32 v[32:33], v[230:231], v[134:135], v[32:33]
	v_pk_fma_f32 v[34:35], v[232:233], v[136:137], v[34:35]
	ds_read_b128 v[230:233], v205 offset:4288
	ds_read_b128 v[234:237], v205 offset:4544
	s_waitcnt lgkmcnt(2)
	s_and_b64 vcc, exec, s[28:29]
	s_cbranch_vccz .Lup_z110
	v_mov_b32_dpp v226, v68 row_shr:1 row_mask:0xf bank_mask:0xf
	v_mov_b32_dpp v227, v69 row_shr:1 row_mask:0xf bank_mask:0xf
	v_mov_b32_dpp v228, v70 row_shr:1 row_mask:0xf bank_mask:0xf
	v_mov_b32_dpp v229, v71 row_shr:1 row_mask:0xf bank_mask:0xf
	v_mov_b32_dpp v222, v72 row_shr:1 row_mask:0xf bank_mask:0xf
	v_mov_b32_dpp v223, v73 row_shr:1 row_mask:0xf bank_mask:0xf
	v_mov_b32_dpp v224, v74 row_shr:1 row_mask:0xf bank_mask:0xf
	v_mov_b32_dpp v225, v75 row_shr:1 row_mask:0xf bank_mask:0xf
	s_branch .Lup_d110
.Lup_z110:
	v_mov_b32_dpp v226, v68 row_shr:1 row_mask:0xf bank_mask:0xf bound_ctrl:1
	v_mov_b32_dpp v227, v69 row_shr:1 row_mask:0xf bank_mask:0xf bound_ctrl:1
	v_mov_b32_dpp v228, v70 row_shr:1 row_mask:0xf bank_mask:0xf bound_ctrl:1
	v_mov_b32_dpp v229, v71 row_shr:1 row_mask:0xf bank_mask:0xf bound_ctrl:1
	v_mov_b32_dpp v222, v72 row_shr:1 row_mask:0xf bank_mask:0xf bound_ctrl:1
	v_mov_b32_dpp v223, v73 row_shr:1 row_mask:0xf bank_mask:0xf bound_ctrl:1
	v_mov_b32_dpp v224, v74 row_shr:1 row_mask:0xf bank_mask:0xf bound_ctrl:1
	v_mov_b32_dpp v225, v75 row_shr:1 row_mask:0xf bank_mask:0xf bound_ctrl:1
.Lup_d110:
	v_pk_fma_f32 v[68:69], v[68:69], v[192:193], v[196:197]
	v_pk_fma_f32 v[70:71], v[70:71], v[194:195], v[198:199]
	v_pk_fma_f32 v[68:69], v[72:73], v[188:189], v[68:69]
	v_pk_fma_f32 v[70:71], v[74:75], v[190:191], v[70:71]
	v_pk_fma_f32 v[68:69], v[76:77], v[184:185], v[68:69]
	v_pk_fma_f32 v[70:71], v[78:79], v[186:187], v[70:71]
	v_pk_fma_f32 v[72:73], v[72:73], v[192:193], v[196:197]
	v_pk_fma_f32 v[74:75], v[74:75], v[194:195], v[198:199]
	v_pk_fma_f32 v[72:73], v[76:77], v[188:189], v[72:73]
	v_pk_fma_f32 v[74:75], v[78:79], v[190:191], v[74:75]
	v_pk_fma_f32 v[72:73], v[80:81], v[184:185], v[72:73]
	v_pk_fma_f32 v[74:75], v[82:83], v[186:187], v[74:75]
	v_pk_fma_f32 v[76:77], v[76:77], v[192:193], v[196:197]
	v_pk_fma_f32 v[78:79], v[78:79], v[194:195], v[198:199]
	v_pk_fma_f32 v[76:77], v[80:81], v[188:189], v[76:77]
	v_pk_fma_f32 v[78:79], v[82:83], v[190:191], v[78:79]
	v_pk_fma_f32 v[76:77], v[226:227], v[184:185], v[76:77]
	v_pk_fma_f32 v[78:79], v[228:229], v[186:187], v[78:79]
	v_pk_fma_f32 v[80:81], v[80:81], v[192:193], v[196:197]
	v_pk_fma_f32 v[82:83], v[82:83], v[194:195], v[198:199]
	v_pk_fma_f32 v[80:81], v[226:227], v[188:189], v[80:81]
	v_pk_fma_f32 v[82:83], v[228:229], v[190:191], v[82:83]
	v_pk_fma_f32 v[80:81], v[222:223], v[184:185], v[80:81]
	v_pk_fma_f32 v[82:83], v[224:225], v[186:187], v[82:83]
	s_and_b64 vcc, exec, s[28:29]
	s_cbranch_vccnz .Lup_nohp110
	s_add_u32 s48, s22, s41
	s_addc_u32 s49, s23, 0
	s_add_u32 s16, s48, 0x5800
	s_addc_u32 s17, s49, 0
	v_cmp_eq_u32_e32 vcc, 0, v157
	s_and_saveexec_b64 s[52:53], vcc
	global_store_dwordx4 v3, v[80:83], s[48:49] offset:528
	global_store_dwordx4 v3, v[76:79], s[16:17] offset:528
	s_mov_b64 exec, s[52:53]
	s_nop 4
.Lup_nohp110:
	v_pk_mul_f32 v[150:151], v[96:97], s[10:11]
	v_pk_mul_f32 v[152:153], v[98:99], s[10:11]
	v_pk_mul_f32 v[158:159], v[92:93], s[10:11]
	v_pk_mul_f32 v[160:161], v[94:95], s[10:11]
	v_exp_f32_e32 v150, v150
	v_exp_f32_e32 v151, v151
	v_exp_f32_e32 v152, v152
	v_exp_f32_e32 v153, v153
	v_exp_f32_e32 v158, v158
	v_exp_f32_e32 v159, v159
	v_exp_f32_e32 v160, v160
	v_exp_f32_e32 v161, v161
	v_pk_add_f32 v[150:151], v[150:151], s[12:13]
	v_pk_add_f32 v[152:153], v[152:153], s[12:13]
	v_pk_add_f32 v[158:159], v[158:159], s[12:13]
	v_pk_add_f32 v[160:161], v[160:161], s[12:13]
	v_rcp_f32_e32 v150, v150
	v_rcp_f32_e32 v151, v151
	v_rcp_f32_e32 v152, v152
	v_rcp_f32_e32 v153, v153
	v_rcp_f32_e32 v158, v158
	v_rcp_f32_e32 v159, v159
	v_rcp_f32_e32 v160, v160
	v_rcp_f32_e32 v161, v161
	v_pk_mul_f32 v[150:151], v[96:97], v[150:151]
	v_pk_mul_f32 v[152:153], v[98:99], v[152:153]
	v_pk_mul_f32 v[158:159], v[92:93], v[158:159]
	v_pk_mul_f32 v[160:161], v[94:95], v[160:161]
	v_pk_mul_f32 v[150:151], v[150:151], v[80:81]
	v_pk_mul_f32 v[152:153], v[152:153], v[82:83]
	v_pk_mul_f32 v[158:159], v[158:159], v[76:77]
	v_pk_mul_f32 v[160:161], v[160:161], v[78:79]
	v_cvt_pk_bf16_f32 v130, v150, v151
	v_cvt_pk_bf16_f32 v131, v152, v153
	v_cvt_pk_bf16_f32 v126, v158, v159
	v_cvt_pk_bf16_f32 v127, v160, v161
	v_pk_mul_f32 v[150:151], v[88:89], s[10:11]
	v_pk_mul_f32 v[152:153], v[90:91], s[10:11]
	v_pk_mul_f32 v[158:159], v[84:85], s[10:11]
	v_pk_mul_f32 v[160:161], v[86:87], s[10:11]
	v_exp_f32_e32 v150, v150
	v_exp_f32_e32 v151, v151
	v_exp_f32_e32 v152, v152
	v_exp_f32_e32 v153, v153
	v_exp_f32_e32 v158, v158
	v_exp_f32_e32 v159, v159
	v_exp_f32_e32 v160, v160
	v_exp_f32_e32 v161, v161
	v_pk_add_f32 v[150:151], v[150:151], s[12:13]
	v_pk_add_f32 v[152:153], v[152:153], s[12:13]
	v_pk_add_f32 v[158:159], v[158:159], s[12:13]
	v_pk_add_f32 v[160:161], v[160:161], s[12:13]
	v_rcp_f32_e32 v150, v150
	v_rcp_f32_e32 v151, v151
	v_rcp_f32_e32 v152, v152
	v_rcp_f32_e32 v153, v153
	v_rcp_f32_e32 v158, v158
	v_rcp_f32_e32 v159, v159
	v_rcp_f32_e32 v160, v160
	v_rcp_f32_e32 v161, v161
	v_pk_mul_f32 v[150:151], v[88:89], v[150:151]
	v_pk_mul_f32 v[152:153], v[90:91], v[152:153]
	v_pk_mul_f32 v[158:159], v[84:85], v[158:159]
	v_pk_mul_f32 v[160:161], v[86:87], v[160:161]
	v_pk_mul_f32 v[150:151], v[150:151], v[72:73]
	v_pk_mul_f32 v[152:153], v[152:153], v[74:75]
	v_pk_mul_f32 v[158:159], v[158:159], v[68:69]
	v_pk_mul_f32 v[160:161], v[160:161], v[70:71]
	v_cvt_pk_bf16_f32 v122, v150, v151
	v_cvt_pk_bf16_f32 v123, v152, v153
	v_cvt_pk_bf16_f32 v118, v158, v159
	v_cvt_pk_bf16_f32 v119, v160, v161
	global_store_dwordx4 v221, v[128:131], s[14:15] offset:0
	global_store_dwordx4 v221, v[124:127], s[14:15] offset:128
	global_store_dwordx4 v221, v[120:123], s[14:15] offset:256
	global_store_dwordx4 v221, v[116:119], s[14:15] offset:384
	s_waitcnt lgkmcnt(0)
	v_mov_b32_dpp v234, v4 row_shr:1 row_mask:0xf bank_mask:0xf
	v_mov_b32_dpp v235, v5 row_shr:1 row_mask:0xf bank_mask:0xf
	v_mov_b32_dpp v236, v6 row_shr:1 row_mask:0xf bank_mask:0xf
	v_mov_b32_dpp v237, v7 row_shr:1 row_mask:0xf bank_mask:0xf
	v_mov_b32_dpp v230, v8 row_shr:1 row_mask:0xf bank_mask:0xf
	v_mov_b32_dpp v231, v9 row_shr:1 row_mask:0xf bank_mask:0xf
	v_mov_b32_dpp v232, v10 row_shr:1 row_mask:0xf bank_mask:0xf
	v_mov_b32_dpp v233, v11 row_shr:1 row_mask:0xf bank_mask:0xf
	s_and_b64 vcc, exec, s[28:29]
	s_cbranch_vccz .Lup_nohc111
	v_pk_mul_f32 v[200:201], v[184:185], v[4:5]
	v_pk_mul_f32 v[202:203], v[186:187], v[6:7]
	v_pk_mul_f32 v[238:239], v[184:185], v[8:9]
	v_pk_mul_f32 v[240:241], v[186:187], v[10:11]
	v_pk_fma_f32 v[238:239], v[188:189], v[4:5], v[238:239]
	v_pk_fma_f32 v[240:241], v[190:191], v[6:7], v[240:241]
	s_add_u32 s48, s24, s41
	s_addc_u32 s49, s25, 0
	s_add_u32 s16, s48, 0x5800
	s_addc_u32 s17, s49, 0
	s_and_saveexec_b64 s[52:53], s[56:57]
	global_store_dwordx4 v3, v[200:203], s[48:49] offset:528
	global_store_dwordx4 v3, v[238:241], s[16:17] offset:528
	s_mov_b64 exec, s[52:53]
.Lup_nohc111:
	v_pk_fma_f32 v[4:5], v[4:5], v[192:193], v[196:197]
	v_pk_fma_f32 v[6:7], v[6:7], v[194:195], v[198:199]
	v_pk_fma_f32 v[4:5], v[8:9], v[188:189], v[4:5]
	v_pk_fma_f32 v[6:7], v[10:11], v[190:191], v[6:7]
	v_pk_fma_f32 v[4:5], v[12:13], v[184:185], v[4:5]
	v_pk_fma_f32 v[6:7], v[14:15], v[186:187], v[6:7]
	v_pk_fma_f32 v[8:9], v[8:9], v[192:193], v[196:197]
	v_pk_fma_f32 v[10:11], v[10:11], v[194:195], v[198:199]
	v_pk_fma_f32 v[8:9], v[12:13], v[188:189], v[8:9]
	v_pk_fma_f32 v[10:11], v[14:15], v[190:191], v[10:11]
	v_pk_fma_f32 v[8:9], v[16:17], v[184:185], v[8:9]
	v_pk_fma_f32 v[10:11], v[18:19], v[186:187], v[10:11]
	v_pk_fma_f32 v[12:13], v[12:13], v[192:193], v[196:197]
	v_pk_fma_f32 v[14:15], v[14:15], v[194:195], v[198:199]
	v_pk_fma_f32 v[12:13], v[16:17], v[188:189], v[12:13]
	v_pk_fma_f32 v[14:15], v[18:19], v[190:191], v[14:15]
	v_pk_fma_f32 v[12:13], v[234:235], v[184:185], v[12:13]
	v_pk_fma_f32 v[14:15], v[236:237], v[186:187], v[14:15]
	v_pk_fma_f32 v[16:17], v[16:17], v[192:193], v[196:197]
	v_pk_fma_f32 v[18:19], v[18:19], v[194:195], v[198:199]
	v_pk_fma_f32 v[16:17], v[234:235], v[188:189], v[16:17]
	v_pk_fma_f32 v[18:19], v[236:237], v[190:191], v[18:19]
	v_pk_fma_f32 v[16:17], v[230:231], v[184:185], v[16:17]
	v_pk_fma_f32 v[18:19], v[232:233], v[186:187], v[18:19]
	v_pk_mul_f32 v[150:151], v[32:33], s[10:11]
	v_pk_mul_f32 v[152:153], v[34:35], s[10:11]
	v_pk_mul_f32 v[158:159], v[28:29], s[10:11]
	v_pk_mul_f32 v[160:161], v[30:31], s[10:11]
	v_exp_f32_e32 v150, v150
	v_exp_f32_e32 v151, v151
	v_exp_f32_e32 v152, v152
	v_exp_f32_e32 v153, v153
	v_exp_f32_e32 v158, v158
	v_exp_f32_e32 v159, v159
	v_exp_f32_e32 v160, v160
	v_exp_f32_e32 v161, v161
	v_pk_add_f32 v[150:151], v[150:151], s[12:13]
	v_pk_add_f32 v[152:153], v[152:153], s[12:13]
	v_pk_add_f32 v[158:159], v[158:159], s[12:13]
	v_pk_add_f32 v[160:161], v[160:161], s[12:13]
	v_rcp_f32_e32 v150, v150
	v_rcp_f32_e32 v151, v151
	v_rcp_f32_e32 v152, v152
	v_rcp_f32_e32 v153, v153
	v_rcp_f32_e32 v158, v158
	v_rcp_f32_e32 v159, v159
	v_rcp_f32_e32 v160, v160
	v_rcp_f32_e32 v161, v161
	v_pk_mul_f32 v[150:151], v[32:33], v[150:151]
	v_pk_mul_f32 v[152:153], v[34:35], v[152:153]
	v_pk_mul_f32 v[158:159], v[28:29], v[158:159]
	v_pk_mul_f32 v[160:161], v[30:31], v[160:161]
	v_pk_mul_f32 v[150:151], v[150:151], v[16:17]
	v_pk_mul_f32 v[152:153], v[152:153], v[18:19]
	v_pk_mul_f32 v[158:159], v[158:159], v[12:13]
	v_pk_mul_f32 v[160:161], v[160:161], v[14:15]
	v_cvt_pk_bf16_f32 v66, v150, v151
	v_cvt_pk_bf16_f32 v67, v152, v153
	v_cvt_pk_bf16_f32 v62, v158, v159
	v_cvt_pk_bf16_f32 v63, v160, v161
	v_pk_mul_f32 v[150:151], v[24:25], s[10:11]
	v_pk_mul_f32 v[152:153], v[26:27], s[10:11]
	v_pk_mul_f32 v[158:159], v[20:21], s[10:11]
	v_pk_mul_f32 v[160:161], v[22:23], s[10:11]
	v_exp_f32_e32 v150, v150
	v_exp_f32_e32 v151, v151
	v_exp_f32_e32 v152, v152
	v_exp_f32_e32 v153, v153
	v_exp_f32_e32 v158, v158
	v_exp_f32_e32 v159, v159
	v_exp_f32_e32 v160, v160
	v_exp_f32_e32 v161, v161
	v_pk_add_f32 v[150:151], v[150:151], s[12:13]
	v_pk_add_f32 v[152:153], v[152:153], s[12:13]
	v_pk_add_f32 v[158:159], v[158:159], s[12:13]
	v_pk_add_f32 v[160:161], v[160:161], s[12:13]
	v_rcp_f32_e32 v150, v150
	v_rcp_f32_e32 v151, v151
	v_rcp_f32_e32 v152, v152
	v_rcp_f32_e32 v153, v153
	v_rcp_f32_e32 v158, v158
	v_rcp_f32_e32 v159, v159
	v_rcp_f32_e32 v160, v160
	v_rcp_f32_e32 v161, v161
	v_pk_mul_f32 v[150:151], v[24:25], v[150:151]
	v_pk_mul_f32 v[152:153], v[26:27], v[152:153]
	v_pk_mul_f32 v[158:159], v[20:21], v[158:159]
	v_pk_mul_f32 v[160:161], v[22:23], v[160:161]
	v_pk_mul_f32 v[150:151], v[150:151], v[8:9]
	v_pk_mul_f32 v[152:153], v[152:153], v[10:11]
	v_pk_mul_f32 v[158:159], v[158:159], v[4:5]
	v_pk_mul_f32 v[160:161], v[160:161], v[6:7]
	v_cvt_pk_bf16_f32 v58, v150, v151
	v_cvt_pk_bf16_f32 v59, v152, v153
	v_cvt_pk_bf16_f32 v54, v158, v159
	v_cvt_pk_bf16_f32 v55, v160, v161
	global_store_dwordx4 v221, v[64:67], s[50:51] offset:0
	global_store_dwordx4 v221, v[60:63], s[50:51] offset:128
	global_store_dwordx4 v221, v[56:59], s[50:51] offset:256
	global_store_dwordx4 v221, v[52:55], s[50:51] offset:384
	s_mov_b64 s[10:11], -1
	s_andn2_b64 vcc, exec, s[8:9]
	s_cbranch_vccnz .LBB0_675
	v_readlane_b32 s8, v253, 13
	v_readlane_b32 s9, v253, 14
	s_andn2_b64 vcc, exec, s[8:9]
	s_cbranch_vccnz .LBB0_674
	s_barrier
	s_branch .LBB0_674
